# peeled first K-iteration for non-first units in in-proj/up GEMMs: C=0 first-touch MFMAs (no acc zeroing), first two DMA waits relaxed by epilogue store count
# speedup vs baseline: 1.0293x; 1.0293x over previous
.LBB0_107:
	s_ashr_i32 s95, s94, 31
	s_lshl_b64 s[6:7], s[94:95], 19
	s_add_u32 s90, s88, s6
	s_addc_u32 s91, s89, s7
	s_and_b64 s[6:7], s[38:39], exec
	s_cselect_b32 s6, s91, s5
	s_cselect_b32 s7, s90, s4
	s_ashr_i32 s37, s36, 31
	s_lshl_b64 s[40:41], s[36:37], 19
	s_add_u32 s96, s86, s40
	s_addc_u32 s97, s87, s41
	s_and_b64 s[40:41], s[38:39], exec
	s_cselect_b32 s37, s97, s1
	s_cselect_b32 s42, s96, s0
	s_add_u32 s40, s4, 0x40080
	s_addc_u32 s41, s5, 0
	s_add_u32 s43, s0, 0x100
	s_addc_u32 s46, s1, 0
	s_mov_b32 s47, -2
	s_cmp_eq_u32 s66, 1
	s_cbranch_scc0 .Lpeel_108
	v_mov_b32_e32 v0, 0
	v_mov_b32_e32 v1, v0
	v_mov_b32_e32 v2, v0
	v_mov_b32_e32 v3, v0
	v_mov_b32_e32 v4, v0
	v_mov_b32_e32 v5, v0
	v_mov_b32_e32 v6, v0
	v_mov_b32_e32 v7, v0
	v_mov_b32_e32 v16, v0
	v_mov_b32_e32 v17, v0
	v_mov_b32_e32 v18, v0
	v_mov_b32_e32 v19, v0
	v_mov_b32_e32 v20, v0
	v_mov_b32_e32 v21, v0
	v_mov_b32_e32 v22, v0
	v_mov_b32_e32 v23, v0
	v_mov_b32_e32 v32, v0
	v_mov_b32_e32 v33, v0
	v_mov_b32_e32 v34, v0
	v_mov_b32_e32 v35, v0
	v_mov_b32_e32 v36, v0
	v_mov_b32_e32 v37, v0
	v_mov_b32_e32 v38, v0
	v_mov_b32_e32 v39, v0
	v_mov_b32_e32 v64, v0
	v_mov_b32_e32 v65, v0
	v_mov_b32_e32 v66, v0
	v_mov_b32_e32 v67, v0
	v_mov_b32_e32 v68, v0
	v_mov_b32_e32 v69, v0
	v_mov_b32_e32 v70, v0
	v_mov_b32_e32 v71, v0
	v_mov_b32_e32 v8, v0
	v_mov_b32_e32 v9, v0
	v_mov_b32_e32 v10, v0
	v_mov_b32_e32 v11, v0
	v_mov_b32_e32 v12, v0
	v_mov_b32_e32 v13, v0
	v_mov_b32_e32 v14, v0
	v_mov_b32_e32 v15, v0
	v_mov_b32_e32 v24, v0
	v_mov_b32_e32 v25, v0
	v_mov_b32_e32 v26, v0
	v_mov_b32_e32 v27, v0
	v_mov_b32_e32 v28, v0
	v_mov_b32_e32 v29, v0
	v_mov_b32_e32 v30, v0
	v_mov_b32_e32 v31, v0
	v_mov_b32_e32 v48, v0
	v_mov_b32_e32 v49, v0
	v_mov_b32_e32 v50, v0
	v_mov_b32_e32 v51, v0
	v_mov_b32_e32 v52, v0
	v_mov_b32_e32 v53, v0
	v_mov_b32_e32 v54, v0
	v_mov_b32_e32 v55, v0
	v_mov_b32_e32 v72, v0
	v_mov_b32_e32 v73, v0
	v_mov_b32_e32 v74, v0
	v_mov_b32_e32 v75, v0
	v_mov_b32_e32 v76, v0
	v_mov_b32_e32 v77, v0
	v_mov_b32_e32 v78, v0
	v_mov_b32_e32 v79, v0
	v_mov_b32_e32 v80, v0
	v_mov_b32_e32 v81, v0
	v_mov_b32_e32 v82, v0
	v_mov_b32_e32 v83, v0
	v_mov_b32_e32 v84, v0
	v_mov_b32_e32 v85, v0
	v_mov_b32_e32 v86, v0
	v_mov_b32_e32 v87, v0
	v_mov_b32_e32 v128, v0
	v_mov_b32_e32 v129, v0
	v_mov_b32_e32 v130, v0
	v_mov_b32_e32 v131, v0
	v_mov_b32_e32 v132, v0
	v_mov_b32_e32 v133, v0
	v_mov_b32_e32 v134, v0
	v_mov_b32_e32 v135, v0
	v_mov_b32_e32 v96, v0
	v_mov_b32_e32 v97, v0
	v_mov_b32_e32 v98, v0
	v_mov_b32_e32 v99, v0
	v_mov_b32_e32 v100, v0
	v_mov_b32_e32 v101, v0
	v_mov_b32_e32 v102, v0
	v_mov_b32_e32 v103, v0
	v_mov_b32_e32 v144, v0
	v_mov_b32_e32 v145, v0
	v_mov_b32_e32 v146, v0
	v_mov_b32_e32 v147, v0
	v_mov_b32_e32 v148, v0
	v_mov_b32_e32 v149, v0
	v_mov_b32_e32 v150, v0
	v_mov_b32_e32 v151, v0
	v_mov_b32_e32 v88, v0
	v_mov_b32_e32 v89, v0
	v_mov_b32_e32 v90, v0
	v_mov_b32_e32 v91, v0
	v_mov_b32_e32 v92, v0
	v_mov_b32_e32 v93, v0
	v_mov_b32_e32 v94, v0
	v_mov_b32_e32 v95, v0
	v_mov_b32_e32 v136, v0
	v_mov_b32_e32 v137, v0
	v_mov_b32_e32 v138, v0
	v_mov_b32_e32 v139, v0
	v_mov_b32_e32 v140, v0
	v_mov_b32_e32 v141, v0
	v_mov_b32_e32 v142, v0
	v_mov_b32_e32 v143, v0
	v_mov_b32_e32 v108, v0
	v_mov_b32_e32 v109, v0
	v_mov_b32_e32 v110, v0
	v_mov_b32_e32 v111, v0
	v_mov_b32_e32 v116, v0
	v_mov_b32_e32 v117, v0
	v_mov_b32_e32 v118, v0
	v_mov_b32_e32 v119, v0
	v_mov_b32_e32 v160, v0
	v_mov_b32_e32 v161, v0
	v_mov_b32_e32 v162, v0
	v_mov_b32_e32 v163, v0
	v_mov_b32_e32 v164, v0
	v_mov_b32_e32 v165, v0
	v_mov_b32_e32 v166, v0
	v_mov_b32_e32 v167, v0
	s_waitcnt vmcnt(0)
	s_branch .LBB0_108
.Lpeel_108:
	s_add_u32 s0, s40, 0xfffc0080
	s_addc_u32 s1, s41, -1
	s_add_i32 s68, 0, 0x10000
	s_cmp_eq_u32 s47, 12
	s_cselect_b32 s5, s6, s1
	s_cselect_b32 s4, s7, s0
	s_cselect_b32 s1, s37, s46
	s_cselect_b32 s0, s42, s43
	s_add_i32 s70, 0, 0x14000
	v_add_u32_e32 v60, s68, v250
	v_add_u32_e32 v124, s70, v250
	ds_read_b128 v[40:43], v60
	ds_read_b128 v[44:47], v60 offset:1024
	ds_read_b128 v[56:59], v60 offset:2048
	ds_read_b128 v[60:63], v60 offset:3072
	ds_read_b128 v[104:107], v124
	ds_read_b128 v[112:115], v124 offset:1024
	ds_read_b128 v[120:123], v124 offset:2048
	ds_read_b128 v[124:127], v124 offset:3072
	s_add_i32 m0, s20, 0xc000
	ds_read_b128 v[152:155], v251
	ds_read_b128 v[156:159], v251 offset:1024
	ds_read_b128 v[168:171], v251 offset:2048
	ds_read_b128 v[172:175], v251 offset:3072
	ds_read_b128 v[200:203], v251 offset:4096
	ds_read_b128 v[204:207], v251 offset:5120
	ds_read_b128 v[208:211], v251 offset:6144
	ds_read_b128 v[212:215], v251 offset:7168
	global_load_lds_dwordx4 v196, s[40:41]
	s_add_i32 m0, s20, 0xe000
	s_nop 0
	global_load_lds_dwordx4 v198, s[40:41]
	s_waitcnt vmcnt(24)
	s_waitcnt lgkmcnt(0)
	s_barrier
	s_setprio 1
	s_waitcnt lgkmcnt(0)
	v_mfma_f32_16x16x32_bf16 v[164:167], v[40:43], v[152:155], 0
	v_mfma_f32_16x16x32_bf16 v[160:163], v[56:59], v[152:155], 0
	v_mfma_f32_16x16x32_bf16 v[116:119], v[40:43], v[168:171], 0
	v_mfma_f32_16x16x32_bf16 v[108:111], v[56:59], v[168:171], 0
	v_mfma_f32_16x16x32_bf16 v[140:143], v[40:43], v[200:203], 0
	v_mfma_f32_16x16x32_bf16 v[136:139], v[56:59], v[200:203], 0
	v_mfma_f32_16x16x32_bf16 v[92:95], v[40:43], v[208:211], 0
	v_mfma_f32_16x16x32_bf16 v[88:91], v[56:59], v[208:211], 0
	v_mfma_f32_16x16x32_bf16 v[164:167], v[44:47], v[156:159], v[164:167]
	v_mfma_f32_16x16x32_bf16 v[160:163], v[60:63], v[156:159], v[160:163]
	v_mfma_f32_16x16x32_bf16 v[116:119], v[44:47], v[172:175], v[116:119]
	v_mfma_f32_16x16x32_bf16 v[108:111], v[60:63], v[172:175], v[108:111]
	v_mfma_f32_16x16x32_bf16 v[140:143], v[44:47], v[204:207], v[140:143]
	v_mfma_f32_16x16x32_bf16 v[136:139], v[60:63], v[204:207], v[136:139]
	v_mfma_f32_16x16x32_bf16 v[92:95], v[44:47], v[212:215], v[92:95]
	v_mfma_f32_16x16x32_bf16 v[88:91], v[60:63], v[212:215], v[88:91]
	s_setprio 0
	s_setprio 1
	v_mfma_f32_16x16x32_bf16 v[148:151], v[104:107], v[152:155], 0
	v_mfma_f32_16x16x32_bf16 v[144:147], v[120:123], v[152:155], 0
	v_mfma_f32_16x16x32_bf16 v[100:103], v[104:107], v[168:171], 0
	v_mfma_f32_16x16x32_bf16 v[96:99], v[120:123], v[168:171], 0
	v_mfma_f32_16x16x32_bf16 v[132:135], v[104:107], v[200:203], 0
	v_mfma_f32_16x16x32_bf16 v[128:131], v[120:123], v[200:203], 0
	v_mfma_f32_16x16x32_bf16 v[84:87], v[104:107], v[208:211], 0
	v_mfma_f32_16x16x32_bf16 v[80:83], v[120:123], v[208:211], 0
	v_mfma_f32_16x16x32_bf16 v[148:151], v[112:115], v[156:159], v[148:151]
	v_mfma_f32_16x16x32_bf16 v[144:147], v[124:127], v[156:159], v[144:147]
	v_mfma_f32_16x16x32_bf16 v[100:103], v[112:115], v[172:175], v[100:103]
	v_mfma_f32_16x16x32_bf16 v[96:99], v[124:127], v[172:175], v[96:99]
	v_mfma_f32_16x16x32_bf16 v[132:135], v[112:115], v[204:207], v[132:135]
	v_mfma_f32_16x16x32_bf16 v[128:131], v[124:127], v[204:207], v[128:131]
	v_mfma_f32_16x16x32_bf16 v[84:87], v[112:115], v[212:215], v[84:87]
	v_mfma_f32_16x16x32_bf16 v[80:83], v[124:127], v[212:215], v[80:83]
	s_setprio 0
	s_barrier
	s_add_i32 s68, s68, s27
	v_lshl_add_u64 v[178:179], s[0:1], 0, v[176:177]
	s_mov_b32 m0, s68
	ds_read_b128 v[152:155], v251 offset:16384
	ds_read_b128 v[156:159], v251 offset:17408
	ds_read_b128 v[168:171], v251 offset:18432
	ds_read_b128 v[172:175], v251 offset:19456
	ds_read_b128 v[200:203], v251 offset:20480
	ds_read_b128 v[204:207], v251 offset:21504
	ds_read_b128 v[208:211], v251 offset:22528
	ds_read_b128 v[212:215], v251 offset:23552
	global_load_lds_dwordx4 v176, s[0:1]
	s_add_i32 m0, s68, 0x2000
	s_add_u32 s68, s0, 0x40000
	v_lshl_add_u64 v[180:181], s[0:1], 0, v[190:191]
	s_addc_u32 s69, s1, 0
	s_add_i32 s70, s70, s27
	global_load_lds_dwordx4 v190, s[0:1]
	s_mov_b32 m0, s70
	v_lshl_add_u64 v[188:189], s[4:5], 0, v[192:193]
	global_load_lds_dwordx4 v176, s[68:69]
	s_add_i32 m0, s70, 0x2000
	s_nop 0
	global_load_lds_dwordx4 v190, s[68:69]
	v_lshl_add_u64 v[186:187], s[4:5], 0, v[194:195]
	s_mov_b32 m0, s20
	s_nop 0
	global_load_lds_dwordx4 v194, s[4:5]
	s_mov_b32 m0, s12
	s_nop 0
	global_load_lds_dwordx4 v192, s[4:5]
	s_waitcnt vmcnt(24)
	s_waitcnt lgkmcnt(0)
	s_barrier
	s_setprio 1
	s_waitcnt lgkmcnt(0)
	v_mfma_f32_16x16x32_bf16 v[76:79], v[40:43], v[152:155], 0
	v_mfma_f32_16x16x32_bf16 v[72:75], v[56:59], v[152:155], 0
	v_mfma_f32_16x16x32_bf16 v[52:55], v[40:43], v[168:171], 0
	v_mfma_f32_16x16x32_bf16 v[48:51], v[56:59], v[168:171], 0
	v_mfma_f32_16x16x32_bf16 v[28:31], v[40:43], v[200:203], 0
	v_mfma_f32_16x16x32_bf16 v[24:27], v[56:59], v[200:203], 0
	v_mfma_f32_16x16x32_bf16 v[12:15], v[40:43], v[208:211], 0
	v_mfma_f32_16x16x32_bf16 v[8:11], v[56:59], v[208:211], 0
	v_mfma_f32_16x16x32_bf16 v[76:79], v[44:47], v[156:159], v[76:79]
	v_mfma_f32_16x16x32_bf16 v[72:75], v[60:63], v[156:159], v[72:75]
	v_mfma_f32_16x16x32_bf16 v[52:55], v[44:47], v[172:175], v[52:55]
	v_mfma_f32_16x16x32_bf16 v[48:51], v[60:63], v[172:175], v[48:51]
	v_mfma_f32_16x16x32_bf16 v[28:31], v[44:47], v[204:207], v[28:31]
	v_mfma_f32_16x16x32_bf16 v[24:27], v[60:63], v[204:207], v[24:27]
	v_mfma_f32_16x16x32_bf16 v[12:15], v[44:47], v[212:215], v[12:15]
	v_mfma_f32_16x16x32_bf16 v[8:11], v[60:63], v[212:215], v[8:11]
	s_setprio 0
	s_setprio 1
	v_mfma_f32_16x16x32_bf16 v[36:39], v[104:107], v[168:171], 0
	v_mfma_f32_16x16x32_bf16 v[32:35], v[120:123], v[168:171], 0
	v_mfma_f32_16x16x32_bf16 v[20:23], v[104:107], v[200:203], 0
	v_mfma_f32_16x16x32_bf16 v[16:19], v[120:123], v[200:203], 0
	v_mfma_f32_16x16x32_bf16 v[4:7], v[104:107], v[208:211], 0
	v_mfma_f32_16x16x32_bf16 v[0:3], v[120:123], v[208:211], 0
	v_mfma_f32_16x16x32_bf16 v[40:43], v[104:107], v[152:155], 0
	v_mfma_f32_16x16x32_bf16 v[44:47], v[120:123], v[152:155], 0
	v_mfma_f32_16x16x32_bf16 v[36:39], v[112:115], v[172:175], v[36:39]
	v_mfma_f32_16x16x32_bf16 v[32:35], v[124:127], v[172:175], v[32:35]
	v_mfma_f32_16x16x32_bf16 v[20:23], v[112:115], v[204:207], v[20:23]
	v_mfma_f32_16x16x32_bf16 v[16:19], v[124:127], v[204:207], v[16:19]
	v_mfma_f32_16x16x32_bf16 v[4:7], v[112:115], v[212:215], v[4:7]
	v_mfma_f32_16x16x32_bf16 v[0:3], v[124:127], v[212:215], v[0:3]
	v_mfma_f32_16x16x32_bf16 v[40:43], v[112:115], v[156:159], v[40:43]
	v_mfma_f32_16x16x32_bf16 v[44:47], v[124:127], v[156:159], v[44:47]
	s_setprio 0
	s_barrier
	s_add_i32 s68, 0, 0x18000
	s_add_i32 s69, 0, 0x1c000
	v_add_u32_e32 v68, s68, v250
	v_add_u32_e32 v124, s69, v250
	ds_read_b128 v[56:59], v68
	ds_read_b128 v[60:63], v68 offset:1024
	ds_read_b128 v[64:67], v68 offset:2048
	ds_read_b128 v[68:71], v68 offset:3072
	ds_read_b128 v[104:107], v124
	ds_read_b128 v[112:115], v124 offset:1024
	ds_read_b128 v[120:123], v124 offset:2048
	ds_read_b128 v[124:127], v124 offset:3072
	s_add_u32 s4, s4, 0x40000
	s_addc_u32 s5, s5, 0
	s_mov_b32 m0, s60
	ds_read_b128 v[152:155], v251 offset:32768
	ds_read_b128 v[156:159], v251 offset:33792
	ds_read_b128 v[168:171], v251 offset:34816
	ds_read_b128 v[172:175], v251 offset:35840
	ds_read_b128 v[200:203], v251 offset:36864
	ds_read_b128 v[204:207], v251 offset:37888
	ds_read_b128 v[208:211], v251 offset:38912
	ds_read_b128 v[212:215], v251 offset:39936
	global_load_lds_dwordx4 v194, s[4:5]
	s_mov_b32 m0, s61
	s_nop 0
	global_load_lds_dwordx4 v192, s[4:5]
	s_waitcnt vmcnt(8)
	s_waitcnt lgkmcnt(0)
	s_barrier
	s_setprio 1
	s_waitcnt lgkmcnt(0)
	v_mfma_f32_16x16x32_bf16 v[164:167], v[56:59], v[152:155], v[164:167]
	v_mfma_f32_16x16x32_bf16 v[160:163], v[64:67], v[152:155], v[160:163]
	v_mfma_f32_16x16x32_bf16 v[116:119], v[56:59], v[168:171], v[116:119]
	v_mfma_f32_16x16x32_bf16 v[108:111], v[64:67], v[168:171], v[108:111]
	v_mfma_f32_16x16x32_bf16 v[140:143], v[56:59], v[200:203], v[140:143]
	v_mfma_f32_16x16x32_bf16 v[136:139], v[64:67], v[200:203], v[136:139]
	v_mfma_f32_16x16x32_bf16 v[92:95], v[56:59], v[208:211], v[92:95]
	v_mfma_f32_16x16x32_bf16 v[88:91], v[64:67], v[208:211], v[88:91]
	v_mfma_f32_16x16x32_bf16 v[164:167], v[60:63], v[156:159], v[164:167]
	v_mfma_f32_16x16x32_bf16 v[160:163], v[68:71], v[156:159], v[160:163]
	v_mfma_f32_16x16x32_bf16 v[116:119], v[60:63], v[172:175], v[116:119]
	v_mfma_f32_16x16x32_bf16 v[108:111], v[68:71], v[172:175], v[108:111]
	v_mfma_f32_16x16x32_bf16 v[140:143], v[60:63], v[204:207], v[140:143]
	v_mfma_f32_16x16x32_bf16 v[136:139], v[68:71], v[204:207], v[136:139]
	v_mfma_f32_16x16x32_bf16 v[92:95], v[60:63], v[212:215], v[92:95]
	v_mfma_f32_16x16x32_bf16 v[88:91], v[68:71], v[212:215], v[88:91]
	s_setprio 0
	s_setprio 1
	v_mfma_f32_16x16x32_bf16 v[148:151], v[104:107], v[152:155], v[148:151]
	v_mfma_f32_16x16x32_bf16 v[144:147], v[120:123], v[152:155], v[144:147]
	v_mfma_f32_16x16x32_bf16 v[100:103], v[104:107], v[168:171], v[100:103]
	v_mfma_f32_16x16x32_bf16 v[96:99], v[120:123], v[168:171], v[96:99]
	v_mfma_f32_16x16x32_bf16 v[132:135], v[104:107], v[200:203], v[132:135]
	v_mfma_f32_16x16x32_bf16 v[128:131], v[120:123], v[200:203], v[128:131]
	v_mfma_f32_16x16x32_bf16 v[84:87], v[104:107], v[208:211], v[84:87]
	v_mfma_f32_16x16x32_bf16 v[80:83], v[120:123], v[208:211], v[80:83]
	v_mfma_f32_16x16x32_bf16 v[148:151], v[112:115], v[156:159], v[148:151]
	v_mfma_f32_16x16x32_bf16 v[144:147], v[124:127], v[156:159], v[144:147]
	v_mfma_f32_16x16x32_bf16 v[100:103], v[112:115], v[172:175], v[100:103]
	v_mfma_f32_16x16x32_bf16 v[96:99], v[124:127], v[172:175], v[96:99]
	v_mfma_f32_16x16x32_bf16 v[132:135], v[112:115], v[204:207], v[132:135]
	v_mfma_f32_16x16x32_bf16 v[128:131], v[124:127], v[204:207], v[128:131]
	v_mfma_f32_16x16x32_bf16 v[84:87], v[112:115], v[212:215], v[84:87]
	v_mfma_f32_16x16x32_bf16 v[80:83], v[124:127], v[212:215], v[80:83]
	s_setprio 0
	s_barrier
	s_add_i32 s4, s68, s27
	v_lshl_add_u64 v[178:179], v[178:179], 0, s[82:83]
	s_mov_b32 m0, s4
	ds_read_b128 v[152:155], v251 offset:49152
	ds_read_b128 v[156:159], v251 offset:50176
	ds_read_b128 v[168:171], v251 offset:51200
	ds_read_b128 v[172:175], v251 offset:52224
	ds_read_b128 v[200:203], v251 offset:53248
	ds_read_b128 v[204:207], v251 offset:54272
	ds_read_b128 v[208:211], v251 offset:55296
	ds_read_b128 v[212:215], v251 offset:56320
	global_load_lds_dwordx4 v[178:179], off
	s_add_i32 m0, s4, 0x2000
	s_add_u32 s0, s0, 0x40080
	v_lshl_add_u64 v[178:179], v[180:181], 0, s[82:83]
	s_addc_u32 s1, s1, 0
	s_add_i32 s4, s69, s27
	global_load_lds_dwordx4 v[178:179], off
	s_mov_b32 m0, s4
	s_nop 0
	global_load_lds_dwordx4 v176, s[0:1]
	s_add_i32 m0, s4, 0x2000
	s_nop 0
	global_load_lds_dwordx4 v190, s[0:1]
	v_lshl_add_u64 v[178:179], v[186:187], 0, s[82:83]
	s_mov_b32 m0, s64
	s_nop 0
	global_load_lds_dwordx4 v[178:179], off
	v_lshl_add_u64 v[178:179], v[188:189], 0, s[82:83]
	s_mov_b32 m0, s65
	s_nop 0
	global_load_lds_dwordx4 v[178:179], off
	s_waitcnt vmcnt(8)
	s_waitcnt lgkmcnt(0)
	s_barrier
	s_setprio 1
	s_waitcnt lgkmcnt(0)
	v_mfma_f32_16x16x32_bf16 v[76:79], v[56:59], v[152:155], v[76:79]
	v_mfma_f32_16x16x32_bf16 v[72:75], v[64:67], v[152:155], v[72:75]
	v_mfma_f32_16x16x32_bf16 v[52:55], v[56:59], v[168:171], v[52:55]
	v_mfma_f32_16x16x32_bf16 v[48:51], v[64:67], v[168:171], v[48:51]
	v_mfma_f32_16x16x32_bf16 v[28:31], v[56:59], v[200:203], v[28:31]
	v_mfma_f32_16x16x32_bf16 v[24:27], v[64:67], v[200:203], v[24:27]
	v_mfma_f32_16x16x32_bf16 v[12:15], v[56:59], v[208:211], v[12:15]
	v_mfma_f32_16x16x32_bf16 v[8:11], v[64:67], v[208:211], v[8:11]
	v_mfma_f32_16x16x32_bf16 v[76:79], v[60:63], v[156:159], v[76:79]
	v_mfma_f32_16x16x32_bf16 v[72:75], v[68:71], v[156:159], v[72:75]
	v_mfma_f32_16x16x32_bf16 v[52:55], v[60:63], v[172:175], v[52:55]
	v_mfma_f32_16x16x32_bf16 v[48:51], v[68:71], v[172:175], v[48:51]
	v_mfma_f32_16x16x32_bf16 v[28:31], v[60:63], v[204:207], v[28:31]
	v_mfma_f32_16x16x32_bf16 v[24:27], v[68:71], v[204:207], v[24:27]
	v_mfma_f32_16x16x32_bf16 v[12:15], v[60:63], v[212:215], v[12:15]
	v_mfma_f32_16x16x32_bf16 v[8:11], v[68:71], v[212:215], v[8:11]
	s_setprio 0
	s_setprio 1
	v_mfma_f32_16x16x32_bf16 v[40:43], v[104:107], v[152:155], v[40:43]
	v_mfma_f32_16x16x32_bf16 v[68:71], v[112:115], v[156:159], v[40:43]
	v_mfma_f32_16x16x32_bf16 v[40:43], v[120:123], v[152:155], v[44:47]
	v_mfma_f32_16x16x32_bf16 v[36:39], v[104:107], v[168:171], v[36:39]
	v_mfma_f32_16x16x32_bf16 v[32:35], v[120:123], v[168:171], v[32:35]
	v_mfma_f32_16x16x32_bf16 v[20:23], v[104:107], v[200:203], v[20:23]
	v_mfma_f32_16x16x32_bf16 v[16:19], v[120:123], v[200:203], v[16:19]
	v_mfma_f32_16x16x32_bf16 v[4:7], v[104:107], v[208:211], v[4:7]
	v_mfma_f32_16x16x32_bf16 v[0:3], v[120:123], v[208:211], v[0:3]
	v_mfma_f32_16x16x32_bf16 v[64:67], v[124:127], v[156:159], v[40:43]
	v_mfma_f32_16x16x32_bf16 v[36:39], v[112:115], v[172:175], v[36:39]
	v_mfma_f32_16x16x32_bf16 v[32:35], v[124:127], v[172:175], v[32:35]
	v_mfma_f32_16x16x32_bf16 v[20:23], v[112:115], v[204:207], v[20:23]
	v_mfma_f32_16x16x32_bf16 v[16:19], v[124:127], v[204:207], v[16:19]
	v_mfma_f32_16x16x32_bf16 v[4:7], v[112:115], v[212:215], v[4:7]
	v_mfma_f32_16x16x32_bf16 v[0:3], v[124:127], v[212:215], v[0:3]
	s_setprio 0
	s_barrier
	s_add_i32 s47, s47, 2
	s_add_u32 s40, s40, 0x100
	s_addc_u32 s41, s41, 0
	s_add_u32 s43, s43, 0x100
	s_addc_u32 s46, s46, 0
	s_cmp_gt_u32 s47, 13

.LBB0_747:
	s_ashr_i32 s39, s38, 31
	s_lshl_b64 s[6:7], s[38:39], 19
	s_add_u32 s88, s12, s6
	s_addc_u32 s89, s20, s7
	s_and_b64 s[6:7], s[42:43], exec
	s_cselect_b32 s6, s89, s5
	s_cselect_b32 s7, s88, s4
	s_ashr_i32 s41, s40, 31
	s_lshl_b64 s[44:45], s[40:41], 19
	s_add_u32 s86, s27, s44
	s_addc_u32 s87, s60, s45
	s_and_b64 s[44:45], s[42:43], exec
	s_cselect_b32 s39, s87, s1
	s_cselect_b32 s41, s86, s0
	s_add_u32 s44, s4, 0x40080
	s_addc_u32 s45, s5, 0
	s_add_u32 s49, s0, 0x100
	s_addc_u32 s72, s1, 0
	s_mov_b32 s73, -2
	s_cmp_eq_u32 s71, 1
	s_cbranch_scc0 .Lpeel_748
	v_mov_b32_e32 v0, 0
	v_mov_b32_e32 v1, v0
	v_mov_b32_e32 v2, v0
	v_mov_b32_e32 v3, v0
	v_mov_b32_e32 v8, v0
	v_mov_b32_e32 v9, v0
	v_mov_b32_e32 v10, v0
	v_mov_b32_e32 v11, v0
	v_mov_b32_e32 v16, v0
	v_mov_b32_e32 v17, v0
	v_mov_b32_e32 v18, v0
	v_mov_b32_e32 v19, v0
	v_mov_b32_e32 v24, v0
	v_mov_b32_e32 v25, v0
	v_mov_b32_e32 v26, v0
	v_mov_b32_e32 v27, v0
	v_mov_b32_e32 v32, v0
	v_mov_b32_e32 v33, v0
	v_mov_b32_e32 v34, v0
	v_mov_b32_e32 v35, v0
	v_mov_b32_e32 v40, v0
	v_mov_b32_e32 v41, v0
	v_mov_b32_e32 v42, v0
	v_mov_b32_e32 v43, v0
	v_mov_b32_e32 v48, v0
	v_mov_b32_e32 v49, v0
	v_mov_b32_e32 v50, v0
	v_mov_b32_e32 v51, v0
	v_mov_b32_e32 v52, v0
	v_mov_b32_e32 v53, v0
	v_mov_b32_e32 v54, v0
	v_mov_b32_e32 v55, v0
	v_mov_b32_e32 v4, v0
	v_mov_b32_e32 v5, v0
	v_mov_b32_e32 v6, v0
	v_mov_b32_e32 v7, v0
	v_mov_b32_e32 v12, v0
	v_mov_b32_e32 v13, v0
	v_mov_b32_e32 v14, v0
	v_mov_b32_e32 v15, v0
	v_mov_b32_e32 v20, v0
	v_mov_b32_e32 v21, v0
	v_mov_b32_e32 v22, v0
	v_mov_b32_e32 v23, v0
	v_mov_b32_e32 v28, v0
	v_mov_b32_e32 v29, v0
	v_mov_b32_e32 v30, v0
	v_mov_b32_e32 v31, v0
	v_mov_b32_e32 v36, v0
	v_mov_b32_e32 v37, v0
	v_mov_b32_e32 v38, v0
	v_mov_b32_e32 v39, v0
	v_mov_b32_e32 v44, v0
	v_mov_b32_e32 v45, v0
	v_mov_b32_e32 v46, v0
	v_mov_b32_e32 v47, v0
	v_mov_b32_e32 v56, v0
	v_mov_b32_e32 v57, v0
	v_mov_b32_e32 v58, v0
	v_mov_b32_e32 v59, v0
	v_mov_b32_e32 v60, v0
	v_mov_b32_e32 v61, v0
	v_mov_b32_e32 v62, v0
	v_mov_b32_e32 v63, v0
	v_mov_b32_e32 v64, v0
	v_mov_b32_e32 v65, v0
	v_mov_b32_e32 v66, v0
	v_mov_b32_e32 v67, v0
	v_mov_b32_e32 v72, v0
	v_mov_b32_e32 v73, v0
	v_mov_b32_e32 v74, v0
	v_mov_b32_e32 v75, v0
	v_mov_b32_e32 v80, v0
	v_mov_b32_e32 v81, v0
	v_mov_b32_e32 v82, v0
	v_mov_b32_e32 v83, v0
	v_mov_b32_e32 v88, v0
	v_mov_b32_e32 v89, v0
	v_mov_b32_e32 v90, v0
	v_mov_b32_e32 v91, v0
	v_mov_b32_e32 v96, v0
	v_mov_b32_e32 v97, v0
	v_mov_b32_e32 v98, v0
	v_mov_b32_e32 v99, v0
	v_mov_b32_e32 v104, v0
	v_mov_b32_e32 v105, v0
	v_mov_b32_e32 v106, v0
	v_mov_b32_e32 v107, v0
	v_mov_b32_e32 v144, v0
	v_mov_b32_e32 v145, v0
	v_mov_b32_e32 v146, v0
	v_mov_b32_e32 v147, v0
	v_mov_b32_e32 v148, v0
	v_mov_b32_e32 v149, v0
	v_mov_b32_e32 v150, v0
	v_mov_b32_e32 v151, v0
	v_mov_b32_e32 v68, v0
	v_mov_b32_e32 v69, v0
	v_mov_b32_e32 v70, v0
	v_mov_b32_e32 v71, v0
	v_mov_b32_e32 v76, v0
	v_mov_b32_e32 v77, v0
	v_mov_b32_e32 v78, v0
	v_mov_b32_e32 v79, v0
	v_mov_b32_e32 v84, v0
	v_mov_b32_e32 v85, v0
	v_mov_b32_e32 v86, v0
	v_mov_b32_e32 v87, v0
	v_mov_b32_e32 v92, v0
	v_mov_b32_e32 v93, v0
	v_mov_b32_e32 v94, v0
	v_mov_b32_e32 v95, v0
	v_mov_b32_e32 v100, v0
	v_mov_b32_e32 v101, v0
	v_mov_b32_e32 v102, v0
	v_mov_b32_e32 v103, v0
	v_mov_b32_e32 v108, v0
	v_mov_b32_e32 v109, v0
	v_mov_b32_e32 v110, v0
	v_mov_b32_e32 v111, v0
	v_mov_b32_e32 v152, v0
	v_mov_b32_e32 v153, v0
	v_mov_b32_e32 v154, v0
	v_mov_b32_e32 v155, v0
	v_mov_b32_e32 v156, v0
	v_mov_b32_e32 v157, v0
	v_mov_b32_e32 v158, v0
	v_mov_b32_e32 v159, v0
	s_waitcnt vmcnt(0)
	s_branch .LBB0_748
.Lpeel_748:
	s_add_u32 s0, s44, 0xfffc0080
	s_addc_u32 s1, s45, -1
	s_add_i32 s74, 0, 0x10000
	s_cmp_eq_u32 s73, 12
	s_cselect_b32 s5, s6, s1
	s_cselect_b32 s4, s7, s0
	s_cselect_b32 s1, s39, s72
	s_cselect_b32 s0, s41, s49
	s_add_i32 s92, 0, 0x14000
	v_add_u32_e32 v124, s74, v199
	v_add_u32_e32 v140, s92, v199
	ds_read_b128 v[112:115], v124
	ds_read_b128 v[116:119], v124 offset:1024
	ds_read_b128 v[120:123], v124 offset:2048
	ds_read_b128 v[124:127], v124 offset:3072
	ds_read_b128 v[128:131], v140
	ds_read_b128 v[132:135], v140 offset:1024
	ds_read_b128 v[136:139], v140 offset:2048
	ds_read_b128 v[140:143], v140 offset:3072
	s_add_i32 m0, s63, 0xc000
	ds_read_b128 v[172:175], v207
	ds_read_b128 v[178:181], v207 offset:1024
	ds_read_b128 v[186:189], v207 offset:2048
	ds_read_b128 v[190:193], v207 offset:3072
	ds_read_b128 v[194:197], v207 offset:4096
	ds_read_b128 v[200:203], v207 offset:5120
	ds_read_b128 v[208:211], v207 offset:6144
	ds_read_b128 v[212:215], v207 offset:7168
	global_load_lds_dwordx4 v168, s[44:45]
	s_add_i32 m0, s63, 0xe000
	s_nop 0
	global_load_lds_dwordx4 v170, s[44:45]
	s_waitcnt vmcnt(18)
	s_waitcnt lgkmcnt(0)
	s_barrier
	s_setprio 1
	s_waitcnt lgkmcnt(0)
	v_mfma_f32_16x16x32_bf16 v[156:159], v[112:115], v[172:175], 0
	v_mfma_f32_16x16x32_bf16 v[152:155], v[120:123], v[172:175], 0
	v_mfma_f32_16x16x32_bf16 v[108:111], v[112:115], v[186:189], 0
	v_mfma_f32_16x16x32_bf16 v[100:103], v[120:123], v[186:189], 0
	v_mfma_f32_16x16x32_bf16 v[92:95], v[112:115], v[194:197], 0
	v_mfma_f32_16x16x32_bf16 v[84:87], v[120:123], v[194:197], 0
	v_mfma_f32_16x16x32_bf16 v[76:79], v[112:115], v[208:211], 0
	v_mfma_f32_16x16x32_bf16 v[68:71], v[120:123], v[208:211], 0
	v_mfma_f32_16x16x32_bf16 v[156:159], v[116:119], v[178:181], v[156:159]
	v_mfma_f32_16x16x32_bf16 v[152:155], v[124:127], v[178:181], v[152:155]
	v_mfma_f32_16x16x32_bf16 v[108:111], v[116:119], v[190:193], v[108:111]
	v_mfma_f32_16x16x32_bf16 v[100:103], v[124:127], v[190:193], v[100:103]
	v_mfma_f32_16x16x32_bf16 v[92:95], v[116:119], v[200:203], v[92:95]
	v_mfma_f32_16x16x32_bf16 v[84:87], v[124:127], v[200:203], v[84:87]
	v_mfma_f32_16x16x32_bf16 v[76:79], v[116:119], v[212:215], v[76:79]
	v_mfma_f32_16x16x32_bf16 v[68:71], v[124:127], v[212:215], v[68:71]
	s_setprio 0
	s_setprio 1
	v_mfma_f32_16x16x32_bf16 v[148:151], v[128:131], v[172:175], 0
	v_mfma_f32_16x16x32_bf16 v[144:147], v[136:139], v[172:175], 0
	v_mfma_f32_16x16x32_bf16 v[104:107], v[128:131], v[186:189], 0
	v_mfma_f32_16x16x32_bf16 v[96:99], v[136:139], v[186:189], 0
	v_mfma_f32_16x16x32_bf16 v[88:91], v[128:131], v[194:197], 0
	v_mfma_f32_16x16x32_bf16 v[80:83], v[136:139], v[194:197], 0
	v_mfma_f32_16x16x32_bf16 v[72:75], v[128:131], v[208:211], 0
	v_mfma_f32_16x16x32_bf16 v[64:67], v[136:139], v[208:211], 0
	v_mfma_f32_16x16x32_bf16 v[148:151], v[132:135], v[178:181], v[148:151]
	v_mfma_f32_16x16x32_bf16 v[144:147], v[140:143], v[178:181], v[144:147]
	v_mfma_f32_16x16x32_bf16 v[104:107], v[132:135], v[190:193], v[104:107]
	v_mfma_f32_16x16x32_bf16 v[96:99], v[140:143], v[190:193], v[96:99]
	v_mfma_f32_16x16x32_bf16 v[88:91], v[132:135], v[200:203], v[88:91]
	v_mfma_f32_16x16x32_bf16 v[80:83], v[140:143], v[200:203], v[80:83]
	v_mfma_f32_16x16x32_bf16 v[72:75], v[132:135], v[212:215], v[72:75]
	v_mfma_f32_16x16x32_bf16 v[64:67], v[140:143], v[212:215], v[64:67]
	s_setprio 0
	s_barrier
	s_add_i32 s74, s74, s62
	v_lshl_add_u64 v[182:183], s[0:1], 0, v[164:165]
	s_mov_b32 m0, s74
	ds_read_b128 v[172:175], v207 offset:16384
	ds_read_b128 v[178:181], v207 offset:17408
	ds_read_b128 v[186:189], v207 offset:18432
	ds_read_b128 v[190:193], v207 offset:19456
	ds_read_b128 v[194:197], v207 offset:20480
	ds_read_b128 v[200:203], v207 offset:21504
	ds_read_b128 v[208:211], v207 offset:22528
	ds_read_b128 v[212:215], v207 offset:23552
	global_load_lds_dwordx4 v164, s[0:1]
	s_add_i32 m0, s74, 0x2000
	s_add_u32 s74, s0, 0x40000
	v_lshl_add_u64 v[204:205], s[0:1], 0, v[160:161]
	s_addc_u32 s75, s1, 0
	s_add_i32 s92, s92, s62
	global_load_lds_dwordx4 v160, s[0:1]
	s_mov_b32 m0, s92
	v_lshl_add_u64 v[218:219], s[4:5], 0, v[162:163]
	global_load_lds_dwordx4 v164, s[74:75]
	s_add_i32 m0, s92, 0x2000
	s_nop 0
	global_load_lds_dwordx4 v160, s[74:75]
	v_lshl_add_u64 v[216:217], s[4:5], 0, v[166:167]
	s_mov_b32 m0, s63
	s_nop 0
	global_load_lds_dwordx4 v166, s[4:5]
	s_mov_b32 m0, s64
	s_nop 0
	global_load_lds_dwordx4 v162, s[4:5]
	s_waitcnt vmcnt(18)
	s_waitcnt lgkmcnt(0)
	s_barrier
	s_setprio 1
	s_waitcnt lgkmcnt(0)
	v_mfma_f32_16x16x32_bf16 v[60:63], v[112:115], v[172:175], 0
	v_mfma_f32_16x16x32_bf16 v[56:59], v[120:123], v[172:175], 0
	v_mfma_f32_16x16x32_bf16 v[44:47], v[112:115], v[186:189], 0
	v_mfma_f32_16x16x32_bf16 v[36:39], v[120:123], v[186:189], 0
	v_mfma_f32_16x16x32_bf16 v[28:31], v[112:115], v[194:197], 0
	v_mfma_f32_16x16x32_bf16 v[20:23], v[120:123], v[194:197], 0
	v_mfma_f32_16x16x32_bf16 v[12:15], v[112:115], v[208:211], 0
	v_mfma_f32_16x16x32_bf16 v[4:7], v[120:123], v[208:211], 0
	v_mfma_f32_16x16x32_bf16 v[60:63], v[116:119], v[178:181], v[60:63]
	v_mfma_f32_16x16x32_bf16 v[56:59], v[124:127], v[178:181], v[56:59]
	v_mfma_f32_16x16x32_bf16 v[44:47], v[116:119], v[190:193], v[44:47]
	v_mfma_f32_16x16x32_bf16 v[36:39], v[124:127], v[190:193], v[36:39]
	v_mfma_f32_16x16x32_bf16 v[28:31], v[116:119], v[200:203], v[28:31]
	v_mfma_f32_16x16x32_bf16 v[20:23], v[124:127], v[200:203], v[20:23]
	v_mfma_f32_16x16x32_bf16 v[12:15], v[116:119], v[212:215], v[12:15]
	v_mfma_f32_16x16x32_bf16 v[4:7], v[124:127], v[212:215], v[4:7]
	s_setprio 0
	s_setprio 1
	v_mfma_f32_16x16x32_bf16 v[52:55], v[128:131], v[172:175], 0
	v_mfma_f32_16x16x32_bf16 v[48:51], v[136:139], v[172:175], 0
	v_mfma_f32_16x16x32_bf16 v[40:43], v[128:131], v[186:189], 0
	v_mfma_f32_16x16x32_bf16 v[32:35], v[136:139], v[186:189], 0
	v_mfma_f32_16x16x32_bf16 v[24:27], v[128:131], v[194:197], 0
	v_mfma_f32_16x16x32_bf16 v[16:19], v[136:139], v[194:197], 0
	v_mfma_f32_16x16x32_bf16 v[8:11], v[128:131], v[208:211], 0
	v_mfma_f32_16x16x32_bf16 v[0:3], v[136:139], v[208:211], 0
	v_mfma_f32_16x16x32_bf16 v[52:55], v[132:135], v[178:181], v[52:55]
	v_mfma_f32_16x16x32_bf16 v[48:51], v[140:143], v[178:181], v[48:51]
	v_mfma_f32_16x16x32_bf16 v[40:43], v[132:135], v[190:193], v[40:43]
	v_mfma_f32_16x16x32_bf16 v[32:35], v[140:143], v[190:193], v[32:35]
	v_mfma_f32_16x16x32_bf16 v[24:27], v[132:135], v[200:203], v[24:27]
	v_mfma_f32_16x16x32_bf16 v[16:19], v[140:143], v[200:203], v[16:19]
	v_mfma_f32_16x16x32_bf16 v[8:11], v[132:135], v[212:215], v[8:11]
	v_mfma_f32_16x16x32_bf16 v[0:3], v[140:143], v[212:215], v[0:3]
	s_setprio 0
	s_barrier
	s_add_i32 s74, 0, 0x18000
	s_add_i32 s75, 0, 0x1c000
	v_add_u32_e32 v124, s74, v199
	v_add_u32_e32 v140, s75, v199
	ds_read_b128 v[112:115], v124
	ds_read_b128 v[116:119], v124 offset:1024
	ds_read_b128 v[120:123], v124 offset:2048
	ds_read_b128 v[124:127], v124 offset:3072
	ds_read_b128 v[128:131], v140
	ds_read_b128 v[132:135], v140 offset:1024
	ds_read_b128 v[136:139], v140 offset:2048
	ds_read_b128 v[140:143], v140 offset:3072
	s_add_u32 s4, s4, 0x40000
	s_addc_u32 s5, s5, 0
	s_mov_b32 m0, s65
	ds_read_b128 v[172:175], v207 offset:32768
	ds_read_b128 v[178:181], v207 offset:33792
	ds_read_b128 v[186:189], v207 offset:34816
	ds_read_b128 v[190:193], v207 offset:35840
	ds_read_b128 v[194:197], v207 offset:36864
	ds_read_b128 v[200:203], v207 offset:37888
	ds_read_b128 v[208:211], v207 offset:38912
	ds_read_b128 v[212:215], v207 offset:39936
	global_load_lds_dwordx4 v166, s[4:5]
	s_mov_b32 m0, s66
	s_nop 0
	global_load_lds_dwordx4 v162, s[4:5]
	s_waitcnt vmcnt(8)
	s_waitcnt lgkmcnt(0)
	s_barrier
	s_setprio 1
	s_waitcnt lgkmcnt(0)
	v_mfma_f32_16x16x32_bf16 v[156:159], v[112:115], v[172:175], v[156:159]
	v_mfma_f32_16x16x32_bf16 v[152:155], v[120:123], v[172:175], v[152:155]
	v_mfma_f32_16x16x32_bf16 v[108:111], v[112:115], v[186:189], v[108:111]
	v_mfma_f32_16x16x32_bf16 v[100:103], v[120:123], v[186:189], v[100:103]
	v_mfma_f32_16x16x32_bf16 v[92:95], v[112:115], v[194:197], v[92:95]
	v_mfma_f32_16x16x32_bf16 v[84:87], v[120:123], v[194:197], v[84:87]
	v_mfma_f32_16x16x32_bf16 v[76:79], v[112:115], v[208:211], v[76:79]
	v_mfma_f32_16x16x32_bf16 v[68:71], v[120:123], v[208:211], v[68:71]
	v_mfma_f32_16x16x32_bf16 v[156:159], v[116:119], v[178:181], v[156:159]
	v_mfma_f32_16x16x32_bf16 v[152:155], v[124:127], v[178:181], v[152:155]
	v_mfma_f32_16x16x32_bf16 v[108:111], v[116:119], v[190:193], v[108:111]
	v_mfma_f32_16x16x32_bf16 v[100:103], v[124:127], v[190:193], v[100:103]
	v_mfma_f32_16x16x32_bf16 v[92:95], v[116:119], v[200:203], v[92:95]
	v_mfma_f32_16x16x32_bf16 v[84:87], v[124:127], v[200:203], v[84:87]
	v_mfma_f32_16x16x32_bf16 v[76:79], v[116:119], v[212:215], v[76:79]
	v_mfma_f32_16x16x32_bf16 v[68:71], v[124:127], v[212:215], v[68:71]
	s_setprio 0
	s_setprio 1
	v_mfma_f32_16x16x32_bf16 v[148:151], v[128:131], v[172:175], v[148:151]
	v_mfma_f32_16x16x32_bf16 v[144:147], v[136:139], v[172:175], v[144:147]
	v_mfma_f32_16x16x32_bf16 v[104:107], v[128:131], v[186:189], v[104:107]
	v_mfma_f32_16x16x32_bf16 v[96:99], v[136:139], v[186:189], v[96:99]
	v_mfma_f32_16x16x32_bf16 v[88:91], v[128:131], v[194:197], v[88:91]
	v_mfma_f32_16x16x32_bf16 v[80:83], v[136:139], v[194:197], v[80:83]
	v_mfma_f32_16x16x32_bf16 v[72:75], v[128:131], v[208:211], v[72:75]
	v_mfma_f32_16x16x32_bf16 v[64:67], v[136:139], v[208:211], v[64:67]
	v_mfma_f32_16x16x32_bf16 v[148:151], v[132:135], v[178:181], v[148:151]
	v_mfma_f32_16x16x32_bf16 v[144:147], v[140:143], v[178:181], v[144:147]
	v_mfma_f32_16x16x32_bf16 v[104:107], v[132:135], v[190:193], v[104:107]
	v_mfma_f32_16x16x32_bf16 v[96:99], v[140:143], v[190:193], v[96:99]
	v_mfma_f32_16x16x32_bf16 v[88:91], v[132:135], v[200:203], v[88:91]
	v_mfma_f32_16x16x32_bf16 v[80:83], v[140:143], v[200:203], v[80:83]
	v_mfma_f32_16x16x32_bf16 v[72:75], v[132:135], v[212:215], v[72:75]
	v_mfma_f32_16x16x32_bf16 v[64:67], v[140:143], v[212:215], v[64:67]
	s_setprio 0
	s_barrier
	s_add_i32 s4, s74, s62
	v_lshl_add_u64 v[182:183], v[182:183], 0, s[82:83]
	s_mov_b32 m0, s4
	ds_read_b128 v[172:175], v207 offset:49152
	ds_read_b128 v[178:181], v207 offset:50176
	ds_read_b128 v[186:189], v207 offset:51200
	ds_read_b128 v[190:193], v207 offset:52224
	ds_read_b128 v[194:197], v207 offset:53248
	ds_read_b128 v[200:203], v207 offset:54272
	ds_read_b128 v[208:211], v207 offset:55296
	ds_read_b128 v[212:215], v207 offset:56320
	global_load_lds_dwordx4 v[182:183], off
	s_add_i32 m0, s4, 0x2000
	s_add_u32 s0, s0, 0x40080
	v_lshl_add_u64 v[182:183], v[204:205], 0, s[82:83]
	s_addc_u32 s1, s1, 0
	s_add_i32 s4, s75, s62
	global_load_lds_dwordx4 v[182:183], off
	s_mov_b32 m0, s4
	s_nop 0
	global_load_lds_dwordx4 v164, s[0:1]
	s_add_i32 m0, s4, 0x2000
	s_nop 0
	global_load_lds_dwordx4 v160, s[0:1]
	v_lshl_add_u64 v[182:183], v[216:217], 0, s[82:83]
	s_mov_b32 m0, s69
	s_nop 0
	global_load_lds_dwordx4 v[182:183], off
	v_lshl_add_u64 v[182:183], v[218:219], 0, s[82:83]
	s_mov_b32 m0, s70
	s_nop 0
	global_load_lds_dwordx4 v[182:183], off
	s_waitcnt vmcnt(8)
	s_waitcnt lgkmcnt(0)
	s_barrier
	s_setprio 1
	s_waitcnt lgkmcnt(0)
	v_mfma_f32_16x16x32_bf16 v[60:63], v[112:115], v[172:175], v[60:63]
	v_mfma_f32_16x16x32_bf16 v[56:59], v[120:123], v[172:175], v[56:59]
	v_mfma_f32_16x16x32_bf16 v[44:47], v[112:115], v[186:189], v[44:47]
	v_mfma_f32_16x16x32_bf16 v[36:39], v[120:123], v[186:189], v[36:39]
	v_mfma_f32_16x16x32_bf16 v[28:31], v[112:115], v[194:197], v[28:31]
	v_mfma_f32_16x16x32_bf16 v[20:23], v[120:123], v[194:197], v[20:23]
	v_mfma_f32_16x16x32_bf16 v[12:15], v[112:115], v[208:211], v[12:15]
	v_mfma_f32_16x16x32_bf16 v[4:7], v[120:123], v[208:211], v[4:7]
	v_mfma_f32_16x16x32_bf16 v[60:63], v[116:119], v[178:181], v[60:63]
	v_mfma_f32_16x16x32_bf16 v[56:59], v[124:127], v[178:181], v[56:59]
	v_mfma_f32_16x16x32_bf16 v[44:47], v[116:119], v[190:193], v[44:47]
	v_mfma_f32_16x16x32_bf16 v[36:39], v[124:127], v[190:193], v[36:39]
	v_mfma_f32_16x16x32_bf16 v[28:31], v[116:119], v[200:203], v[28:31]
	v_mfma_f32_16x16x32_bf16 v[20:23], v[124:127], v[200:203], v[20:23]
	v_mfma_f32_16x16x32_bf16 v[12:15], v[116:119], v[212:215], v[12:15]
	v_mfma_f32_16x16x32_bf16 v[4:7], v[124:127], v[212:215], v[4:7]
	s_setprio 0
	s_setprio 1
	v_mfma_f32_16x16x32_bf16 v[52:55], v[128:131], v[172:175], v[52:55]
	v_mfma_f32_16x16x32_bf16 v[48:51], v[136:139], v[172:175], v[48:51]
	v_mfma_f32_16x16x32_bf16 v[40:43], v[128:131], v[186:189], v[40:43]
	v_mfma_f32_16x16x32_bf16 v[32:35], v[136:139], v[186:189], v[32:35]
	v_mfma_f32_16x16x32_bf16 v[24:27], v[128:131], v[194:197], v[24:27]
	v_mfma_f32_16x16x32_bf16 v[16:19], v[136:139], v[194:197], v[16:19]
	v_mfma_f32_16x16x32_bf16 v[8:11], v[128:131], v[208:211], v[8:11]
	v_mfma_f32_16x16x32_bf16 v[0:3], v[136:139], v[208:211], v[0:3]
	v_mfma_f32_16x16x32_bf16 v[52:55], v[132:135], v[178:181], v[52:55]
	v_mfma_f32_16x16x32_bf16 v[48:51], v[140:143], v[178:181], v[48:51]
	v_mfma_f32_16x16x32_bf16 v[40:43], v[132:135], v[190:193], v[40:43]
	v_mfma_f32_16x16x32_bf16 v[32:35], v[140:143], v[190:193], v[32:35]
	v_mfma_f32_16x16x32_bf16 v[24:27], v[132:135], v[200:203], v[24:27]
	v_mfma_f32_16x16x32_bf16 v[16:19], v[140:143], v[200:203], v[16:19]
	v_mfma_f32_16x16x32_bf16 v[8:11], v[132:135], v[212:215], v[8:11]
	v_mfma_f32_16x16x32_bf16 v[0:3], v[140:143], v[212:215], v[0:3]
	s_setprio 0
	s_barrier
	s_add_i32 s73, s73, 2
	s_add_u32 s44, s44, 0x100
	s_addc_u32 s45, s45, 0
	s_add_u32 s49, s49, 0x100
	s_addc_u32 s72, s72, 0
	s_cmp_gt_u32 s73, 13
